# P0 rmsnorm rows: gain vector held in registers across rows, per-chunk store/load/wait round trips removed; on top of v27
# speedup vs baseline: 1.0157x; 1.0013x over previous
.LBB0_15:
	s_cmpk_gt_i32 s82, 0x20ff
	s_cbranch_scc1 .LBB0_20
	s_waitcnt lgkmcnt(0)
	s_add_u32 s2, s12, 0x18400000
	s_addc_u32 s3, s13, 0
	s_ashr_i32 s83, s82, 31
	v_mbcnt_lo_u32_b32 v1, -1, 0
	s_ashr_i32 s85, s84, 31
	s_lshl_b64 s[12:13], s[82:83], 14
	v_mbcnt_hi_u32_b32 v1, -1, v1
	s_add_u32 s12, s4, s12
	v_and_b32_e32 v2, 64, v1
	s_addc_u32 s13, s5, s13
	s_lshl_b64 s[14:15], s[84:85], 14
	s_movk_i32 s22, 0x2000
	s_mov_b32 s17, 0
	v_mov_b32_e32 v67, 0
	s_movk_i32 s23, 0x1000
	s_movk_i32 s24, 0x3000
	v_add_u32_e32 v68, 64, v2
	v_xor_b32_e32 v69, 1, v1
	v_xor_b32_e32 v70, 2, v1
	v_xor_b32_e32 v71, 4, v1
	v_xor_b32_e32 v72, 8, v1
	v_xor_b32_e32 v73, 16, v1
	v_xor_b32_e32 v74, 32, v1
	v_mov_b32_e32 v75, 0x358637bd
	s_mov_b32 s25, 0xf800000
	v_mov_b32_e32 v76, 0x260
	s_movk_i32 s26, 0x7fff
	s_mov_b32 s27, 0xffff0000
	s_mov_b64 s[18:19], s[82:83]
	v_and_b32_e32 v164, 63, v0
	v_lshlrev_b32_e32 v164, 4, v164
	v_add_u32_e32 v165, 0x1000, v164
	v_add_u32_e32 v166, 0x2000, v164
	v_add_u32_e32 v167, 0x3000, v164
	global_load_dwordx4 v[104:107], v164, s[10:11] offset:1024
	global_load_dwordx4 v[108:111], v164, s[10:11] offset:2048
	global_load_dwordx4 v[112:115], v164, s[10:11] offset:3072
	global_load_dwordx4 v[116:119], v165, s[10:11]
	global_load_dwordx4 v[120:123], v165, s[10:11] offset:1024
	global_load_dwordx4 v[124:127], v165, s[10:11] offset:2048
	global_load_dwordx4 v[128:131], v165, s[10:11] offset:3072
	global_load_dwordx4 v[132:135], v166, s[10:11]
	global_load_dwordx4 v[136:139], v166, s[10:11] offset:1024
	global_load_dwordx4 v[140:143], v166, s[10:11] offset:2048
	global_load_dwordx4 v[144:147], v166, s[10:11] offset:3072
	global_load_dwordx4 v[148:151], v167, s[10:11]
	global_load_dwordx4 v[152:155], v167, s[10:11] offset:1024
	global_load_dwordx4 v[156:159], v167, s[10:11] offset:2048
	global_load_dwordx4 v[160:163], v167, s[10:11] offset:3072
	s_branch .LBB0_18
.LBB0_17:
	v_mov_b32_e32 v2, v0
	s_nop 0
	v_and_b32_e32 v78, 63, v2
	v_lshlrev_b32_e32 v66, 4, v78
	v_lshl_add_u64 v[2:3], s[4:5], 0, v[66:67]
	v_add_co_u32_e32 v4, vcc, s22, v2
	global_load_dwordx4 v[62:65], v66, s[4:5]
	global_load_dwordx4 v[58:61], v66, s[4:5] offset:1024
	global_load_dwordx4 v[54:57], v66, s[4:5] offset:2048
	global_load_dwordx4 v[46:49], v66, s[4:5] offset:3072
	v_addc_co_u32_e32 v5, vcc, 0, v3, vcc
	global_load_dwordx4 v[34:37], v[4:5], off offset:-4096
	v_add_co_u32_e32 v6, vcc, s23, v2
	s_waitcnt vmcnt(4)
	v_mul_f32_e32 v77, v63, v63
	v_addc_co_u32_e32 v7, vcc, 0, v3, vcc
	global_load_dwordx4 v[30:33], v[6:7], off offset:1024
	global_load_dwordx4 v[22:25], v[6:7], off offset:2048
	global_load_dwordx4 v[10:13], v[6:7], off offset:3072
	global_load_dwordx4 v[50:53], v[4:5], off
	global_load_dwordx4 v[42:45], v[4:5], off offset:1024
	global_load_dwordx4 v[38:41], v[4:5], off offset:2048
	global_load_dwordx4 v[26:29], v[4:5], off offset:3072
	v_add_co_u32_e32 v84, vcc, s24, v2
	v_mul_f32_e32 v79, v65, v65
	s_nop 0
	v_addc_co_u32_e32 v85, vcc, 0, v3, vcc
	global_load_dwordx4 v[18:21], v[84:85], off
	global_load_dwordx4 v[80:83], v66, s[10:11]
	global_load_dwordx4 v[14:17], v[84:85], off offset:1024
	global_load_dwordx4 v[6:9], v[84:85], off offset:2048
	global_load_dwordx4 v[2:5], v[84:85], off offset:3072
	s_waitcnt vmcnt(15)
	v_mul_f32_e32 v84, v59, v59
	v_mul_f32_e32 v85, v61, v61
	s_waitcnt vmcnt(14)
	v_mul_f32_e32 v86, v55, v55
	v_mul_f32_e32 v87, v57, v57
	v_fmac_f32_e32 v77, v62, v62
	v_fmac_f32_e32 v79, v64, v64
	v_fmac_f32_e32 v84, v58, v58
	v_fmac_f32_e32 v85, v60, v60
	s_waitcnt vmcnt(13)
	v_mul_f32_e32 v88, v47, v47
	v_mul_f32_e32 v89, v49, v49
	v_fmac_f32_e32 v86, v54, v54
	v_fmac_f32_e32 v87, v56, v56
	v_add_f32_e32 v77, v77, v79
	v_add_f32_e32 v79, v84, v85
	v_fmac_f32_e32 v88, v46, v46
	v_fmac_f32_e32 v89, v48, v48
	v_add_f32_e32 v84, v86, v87
	s_waitcnt vmcnt(12)
	v_mul_f32_e32 v86, v35, v35
	v_mul_f32_e32 v87, v37, v37
	v_add_f32_e32 v77, v77, v79
	v_add_f32_e32 v85, v88, v89
	v_fmac_f32_e32 v86, v34, v34
	v_fmac_f32_e32 v87, v36, v36
	v_add_f32_e32 v77, v77, v84
	v_add_f32_e32 v79, v86, v87
	v_add_f32_e32 v77, v77, v85
	v_add_f32_e32 v77, v77, v79
	v_cmp_lt_i32_e32 vcc, v69, v68
	s_waitcnt vmcnt(11)
	v_mul_f32_e32 v88, v31, v31
	v_mul_f32_e32 v89, v33, v33
	s_waitcnt vmcnt(10)
	v_mul_f32_e32 v90, v23, v23
	v_mul_f32_e32 v91, v25, v25
	v_fmac_f32_e32 v88, v30, v30
	v_fmac_f32_e32 v89, v32, v32
	s_waitcnt vmcnt(9)
	v_mul_f32_e32 v92, v11, v11
	v_mul_f32_e32 v93, v13, v13
	v_fmac_f32_e32 v90, v22, v22
	v_fmac_f32_e32 v91, v24, v24
	v_add_f32_e32 v84, v88, v89
	s_waitcnt vmcnt(8)
	v_mul_f32_e32 v94, v51, v51
	v_mul_f32_e32 v95, v53, v53
	v_fmac_f32_e32 v92, v10, v10
	v_fmac_f32_e32 v93, v12, v12
	v_add_f32_e32 v86, v90, v91
	v_add_f32_e32 v77, v77, v84
	s_waitcnt vmcnt(7)
	v_mul_f32_e32 v96, v43, v43
	v_mul_f32_e32 v97, v45, v45
	v_fmac_f32_e32 v94, v50, v50
	v_fmac_f32_e32 v95, v52, v52
	v_add_f32_e32 v87, v92, v93
	v_add_f32_e32 v77, v77, v86
	s_waitcnt vmcnt(6)
	v_mul_f32_e32 v98, v39, v39
	v_mul_f32_e32 v99, v41, v41
	v_fmac_f32_e32 v96, v42, v42
	v_fmac_f32_e32 v97, v44, v44
	v_add_f32_e32 v88, v94, v95
	v_add_f32_e32 v77, v77, v87
	v_fmac_f32_e32 v98, v38, v38
	v_add_f32_e32 v89, v96, v97
	v_fmac_f32_e32 v99, v40, v40
	v_add_f32_e32 v77, v77, v88
	s_waitcnt vmcnt(5)
	v_mul_f32_e32 v79, v27, v27
	v_mul_f32_e32 v84, v29, v29
	v_add_f32_e32 v90, v98, v99
	v_add_f32_e32 v77, v77, v89
	v_fmac_f32_e32 v79, v26, v26
	v_fmac_f32_e32 v84, v28, v28
	v_add_f32_e32 v77, v77, v90
	v_add_f32_e32 v79, v79, v84
	v_add_f32_e32 v77, v77, v79
	s_waitcnt vmcnt(4)
	v_mul_f32_e32 v79, v19, v19
	v_mul_f32_e32 v84, v21, v21
	v_fmac_f32_e32 v79, v18, v18
	v_fmac_f32_e32 v84, v20, v20
	v_add_f32_e32 v79, v79, v84
	v_add_f32_e32 v77, v77, v79
	s_waitcnt vmcnt(2)
	v_mul_f32_e32 v79, v15, v15
	v_mul_f32_e32 v84, v17, v17
	v_fmac_f32_e32 v79, v14, v14
	v_fmac_f32_e32 v84, v16, v16
	v_add_f32_e32 v79, v79, v84
	v_add_f32_e32 v77, v77, v79
	s_waitcnt vmcnt(1)
	v_mul_f32_e32 v79, v7, v7
	v_mul_f32_e32 v84, v9, v9
	v_fmac_f32_e32 v79, v6, v6
	v_fmac_f32_e32 v84, v8, v8
	v_add_f32_e32 v79, v79, v84
	v_add_f32_e32 v77, v77, v79
	s_waitcnt vmcnt(0)
	v_mul_f32_e32 v79, v3, v3
	v_mul_f32_e32 v84, v5, v5
	v_fmac_f32_e32 v79, v2, v2
	v_fmac_f32_e32 v84, v4, v4
	v_add_f32_e32 v79, v79, v84
	v_add_f32_e32 v77, v77, v79
	v_cndmask_b32_e32 v79, v1, v69, vcc
	v_lshlrev_b32_e32 v79, 2, v79
	ds_bpermute_b32 v79, v79, v77
	v_cmp_lt_i32_e32 vcc, v70, v68
	s_waitcnt lgkmcnt(0)
	v_add_f32_e32 v77, v77, v79
	v_cndmask_b32_e32 v79, v1, v70, vcc
	v_lshlrev_b32_e32 v79, 2, v79
	ds_bpermute_b32 v79, v79, v77
	v_cmp_lt_i32_e32 vcc, v71, v68
	s_waitcnt lgkmcnt(0)
	v_add_f32_e32 v77, v77, v79
	v_cndmask_b32_e32 v79, v1, v71, vcc
	v_lshlrev_b32_e32 v79, 2, v79
	ds_bpermute_b32 v79, v79, v77
	v_cmp_lt_i32_e32 vcc, v72, v68
	s_waitcnt lgkmcnt(0)
	v_add_f32_e32 v77, v77, v79
	v_cndmask_b32_e32 v79, v1, v72, vcc
	v_lshlrev_b32_e32 v79, 2, v79
	ds_bpermute_b32 v79, v79, v77
	v_cmp_lt_i32_e32 vcc, v73, v68
	s_waitcnt lgkmcnt(0)
	v_add_f32_e32 v77, v77, v79
	v_cndmask_b32_e32 v79, v1, v73, vcc
	v_lshlrev_b32_e32 v79, 2, v79
	ds_bpermute_b32 v79, v79, v77
	v_cmp_lt_i32_e32 vcc, v74, v68
	s_waitcnt lgkmcnt(0)
	v_add_f32_e32 v77, v77, v79
	v_cndmask_b32_e32 v79, v1, v74, vcc
	v_lshlrev_b32_e32 v79, 2, v79
	ds_bpermute_b32 v79, v79, v77
	s_waitcnt lgkmcnt(0)
	v_add_f32_e32 v77, v77, v79
	v_fmamk_f32 v77, v77, 0x39800000, v75
	v_mul_f32_e32 v79, 0x4f800000, v77
	v_cmp_gt_f32_e32 vcc, s25, v77
	s_nop 1
	v_cndmask_b32_e32 v77, v77, v79, vcc
	v_sqrt_f32_e32 v79, v77
	s_nop 0
	v_add_u32_e32 v84, -1, v79
	v_fma_f32 v85, -v84, v79, v77
	v_cmp_ge_f32_e64 s[4:5], 0, v85
	v_add_u32_e32 v85, 1, v79
	s_nop 0
	v_cndmask_b32_e64 v84, v79, v84, s[4:5]
	v_fma_f32 v79, -v85, v79, v77
	v_cmp_lt_f32_e64 s[4:5], 0, v79
	s_nop 1
	v_cndmask_b32_e64 v79, v84, v85, s[4:5]
	v_mul_f32_e32 v84, 0x37800000, v79
	v_cndmask_b32_e32 v79, v79, v84, vcc
	v_cmp_class_f32_e32 vcc, v77, v76
	s_nop 1
	v_cndmask_b32_e32 v77, v79, v77, vcc
	v_div_scale_f32 v79, s[4:5], v77, v77, 1.0
	v_rcp_f32_e32 v84, v79
	s_lshl_b64 s[4:5], s[20:21], 13
	s_add_u32 s4, s2, s4
	s_addc_u32 s5, s3, s5
	v_fma_f32 v85, -v79, v84, 1.0
	v_fmac_f32_e32 v84, v85, v84
	v_div_scale_f32 v85, vcc, 1.0, v77, 1.0
	v_mul_f32_e32 v86, v85, v84
	v_fma_f32 v87, -v79, v86, v85
	v_fmac_f32_e32 v86, v87, v84
	v_fma_f32 v79, -v79, v86, v85
	v_div_fmas_f32 v79, v79, v84, v86
	v_div_fixup_f32 v77, v79, v77, 1.0
	v_mul_f32_e32 v62, v62, v77
	v_mul_f32_e32 v63, v63, v77
	v_mul_f32_e32 v62, v80, v62
	v_mul_f32_e32 v64, v64, v77
	v_mul_f32_e32 v63, v81, v63
	v_bfe_u32 v79, v62, 16, 1
	v_mul_f32_e32 v65, v65, v77
	v_mul_f32_e32 v64, v82, v64
	v_add3_u32 v62, v62, v79, s26
	v_bfe_u32 v79, v63, 16, 1
	v_mul_f32_e32 v65, v83, v65
	v_add3_u32 v63, v63, v79, s26
	v_bfe_u32 v79, v64, 16, 1
	v_add3_u32 v79, v64, v79, s26
	v_bfe_u32 v64, v65, 16, 1
	v_lshrrev_b32_e32 v62, 16, v62
	v_add3_u32 v65, v65, v64, s26
	v_and_or_b32 v64, v63, s27, v62
	v_lshrrev_b32_e32 v62, 16, v79
	v_and_or_b32 v65, v65, s27, v62
	v_lshlrev_b32_e32 v62, 3, v78
	global_store_dwordx2 v62, v[64:65], s[4:5]
	v_mov_b32_e32 v78, v104
	v_mov_b32_e32 v79, v105
	v_mov_b32_e32 v80, v106
	v_mov_b32_e32 v81, v107
	v_mul_f32_e32 v58, v58, v77
	v_mul_f32_e32 v60, v60, v77
	v_mul_f32_e32 v59, v59, v77
	v_mul_f32_e32 v61, v61, v77
	v_mul_f32_e32 v54, v54, v77
	v_mul_f32_e32 v56, v56, v77
	v_mul_f32_e32 v55, v55, v77
	v_mul_f32_e32 v57, v57, v77
	v_mul_f32_e32 v46, v46, v77
	v_mul_f32_e32 v48, v48, v77
	v_mul_f32_e32 v47, v47, v77
	v_mul_f32_e32 v49, v49, v77
	v_mul_f32_e32 v34, v34, v77
	v_mul_f32_e32 v36, v36, v77
	v_mul_f32_e32 v35, v35, v77
	v_mul_f32_e32 v37, v37, v77
	v_mul_f32_e32 v30, v30, v77
	v_mul_f32_e32 v32, v32, v77
	v_mul_f32_e32 v31, v31, v77
	v_mul_f32_e32 v33, v33, v77
	v_mul_f32_e32 v22, v22, v77
	v_mul_f32_e32 v24, v24, v77
	v_mul_f32_e32 v23, v23, v77
	v_mul_f32_e32 v25, v25, v77
	v_mul_f32_e32 v10, v10, v77
	v_mul_f32_e32 v12, v12, v77
	v_mul_f32_e32 v11, v11, v77
	v_mul_f32_e32 v13, v13, v77
	v_mul_f32_e32 v6, v6, v77
	v_mul_f32_e32 v8, v8, v77
	v_mul_f32_e32 v7, v7, v77
	v_mul_f32_e32 v9, v9, v77
	v_mul_f32_e32 v2, v2, v77
	v_mul_f32_e32 v4, v4, v77
	s_add_u32 s18, s18, s84
	v_mul_f32_e32 v3, v3, v77
	v_mul_f32_e32 v5, v5, v77
	s_addc_u32 s19, s19, s85
	s_add_u32 s12, s12, s14
	s_addc_u32 s13, s13, s15
	s_cmpk_gt_i32 s18, 0x20ff
	v_mul_f32_e32 v58, v78, v58
	v_mul_f32_e32 v60, v80, v60
	v_mul_f32_e32 v59, v79, v59
	v_mul_f32_e32 v61, v81, v61
	v_bfe_u32 v63, v58, 16, 1
	v_bfe_u32 v65, v60, 16, 1
	v_bfe_u32 v64, v59, 16, 1
	v_bfe_u32 v78, v61, 16, 1
	v_add3_u32 v58, v58, v63, s26
	v_add3_u32 v60, v60, v65, s26
	v_add3_u32 v59, v59, v64, s26
	v_add3_u32 v61, v61, v78, s26
	v_lshrrev_b32_e32 v58, 16, v58
	v_lshrrev_b32_e32 v60, 16, v60
	v_and_or_b32 v58, v59, s27, v58
	v_and_or_b32 v59, v61, s27, v60
	global_store_dwordx2 v62, v[58:59], s[4:5] offset:512
	v_mov_b32_e32 v58, v108
	v_mov_b32_e32 v59, v109
	v_mov_b32_e32 v60, v110
	v_mov_b32_e32 v61, v111
	v_mov_b32_e32 v63, v67
	v_mul_f32_e32 v54, v58, v54
	v_mul_f32_e32 v56, v60, v56
	v_mul_f32_e32 v55, v59, v55
	v_mul_f32_e32 v57, v61, v57
	v_bfe_u32 v58, v54, 16, 1
	v_bfe_u32 v60, v56, 16, 1
	v_bfe_u32 v59, v55, 16, 1
	v_bfe_u32 v61, v57, 16, 1
	v_add3_u32 v54, v54, v58, s26
	v_add3_u32 v56, v56, v60, s26
	v_add3_u32 v55, v55, v59, s26
	v_add3_u32 v57, v57, v61, s26
	v_lshrrev_b32_e32 v54, 16, v54
	v_lshrrev_b32_e32 v56, 16, v56
	v_and_or_b32 v54, v55, s27, v54
	v_and_or_b32 v55, v57, s27, v56
	global_store_dwordx2 v62, v[54:55], s[4:5] offset:1024
	v_mov_b32_e32 v58, v112
	v_mov_b32_e32 v59, v113
	v_mov_b32_e32 v60, v114
	v_mov_b32_e32 v61, v115
	v_lshl_add_u64 v[54:55], s[10:11], 0, v[66:67]
	v_add_co_u32_e32 v56, vcc, s22, v54
	v_mul_f32_e32 v46, v58, v46
	v_mul_f32_e32 v48, v60, v48
	v_mul_f32_e32 v47, v59, v47
	v_mul_f32_e32 v49, v61, v49
	v_bfe_u32 v58, v46, 16, 1
	v_bfe_u32 v60, v48, 16, 1
	v_bfe_u32 v59, v47, 16, 1
	v_bfe_u32 v61, v49, 16, 1
	v_add3_u32 v46, v46, v58, s26
	v_add3_u32 v48, v48, v60, s26
	v_add3_u32 v47, v47, v59, s26
	v_add3_u32 v49, v49, v61, s26
	v_lshrrev_b32_e32 v46, 16, v46
	v_lshrrev_b32_e32 v48, 16, v48
	v_and_or_b32 v46, v47, s27, v46
	v_and_or_b32 v47, v49, s27, v48
	v_addc_co_u32_e32 v57, vcc, 0, v55, vcc
	global_store_dwordx2 v62, v[46:47], s[4:5] offset:1536
	v_mov_b32_e32 v46, v116
	v_mov_b32_e32 v47, v117
	v_mov_b32_e32 v48, v118
	v_mov_b32_e32 v49, v119
	v_add_co_u32_e32 v58, vcc, s23, v54
	v_mul_f32_e32 v34, v34, v46
	v_mul_f32_e32 v36, v36, v48
	v_mul_f32_e32 v35, v35, v47
	v_mul_f32_e32 v37, v37, v49
	v_bfe_u32 v46, v34, 16, 1
	v_bfe_u32 v48, v36, 16, 1
	v_bfe_u32 v47, v35, 16, 1
	v_bfe_u32 v49, v37, 16, 1
	v_add3_u32 v34, v34, v46, s26
	v_add3_u32 v36, v36, v48, s26
	v_add3_u32 v35, v35, v47, s26
	v_add3_u32 v37, v37, v49, s26
	v_lshrrev_b32_e32 v34, 16, v34
	v_lshrrev_b32_e32 v36, 16, v36
	v_and_or_b32 v34, v35, s27, v34
	v_and_or_b32 v35, v37, s27, v36
	v_addc_co_u32_e32 v59, vcc, 0, v55, vcc
	global_store_dwordx2 v62, v[34:35], s[4:5] offset:2048
	v_mov_b32_e32 v34, v120
	v_mov_b32_e32 v35, v121
	v_mov_b32_e32 v36, v122
	v_mov_b32_e32 v37, v123
	v_mul_f32_e32 v30, v30, v34
	v_mul_f32_e32 v32, v32, v36
	v_mul_f32_e32 v31, v31, v35
	v_mul_f32_e32 v33, v33, v37
	v_bfe_u32 v34, v30, 16, 1
	v_bfe_u32 v36, v32, 16, 1
	v_bfe_u32 v35, v31, 16, 1
	v_bfe_u32 v37, v33, 16, 1
	v_add3_u32 v30, v30, v34, s26
	v_add3_u32 v32, v32, v36, s26
	v_add3_u32 v31, v31, v35, s26
	v_add3_u32 v33, v33, v37, s26
	v_lshrrev_b32_e32 v30, 16, v30
	v_lshrrev_b32_e32 v32, 16, v32
	v_and_or_b32 v30, v31, s27, v30
	v_and_or_b32 v31, v33, s27, v32
	global_store_dwordx2 v62, v[30:31], s[4:5] offset:2560
	v_mov_b32_e32 v30, v124
	v_mov_b32_e32 v31, v125
	v_mov_b32_e32 v32, v126
	v_mov_b32_e32 v33, v127
	v_mul_f32_e32 v22, v22, v30
	v_mul_f32_e32 v24, v24, v32
	v_mul_f32_e32 v23, v23, v31
	v_mul_f32_e32 v25, v25, v33
	v_bfe_u32 v30, v22, 16, 1
	v_bfe_u32 v32, v24, 16, 1
	v_bfe_u32 v31, v23, 16, 1
	v_bfe_u32 v33, v25, 16, 1
	v_add3_u32 v22, v22, v30, s26
	v_add3_u32 v24, v24, v32, s26
	v_add3_u32 v23, v23, v31, s26
	v_add3_u32 v25, v25, v33, s26
	v_lshrrev_b32_e32 v22, 16, v22
	v_lshrrev_b32_e32 v24, 16, v24
	v_and_or_b32 v22, v23, s27, v22
	v_and_or_b32 v23, v25, s27, v24
	global_store_dwordx2 v62, v[22:23], s[4:5] offset:3072
	v_mov_b32_e32 v22, v128
	v_mov_b32_e32 v23, v129
	v_mov_b32_e32 v24, v130
	v_mov_b32_e32 v25, v131
	v_mul_f32_e32 v30, v52, v77
	v_mul_f32_e32 v31, v53, v77
	v_mul_f32_e32 v10, v10, v22
	v_mul_f32_e32 v12, v12, v24
	v_mul_f32_e32 v11, v11, v23
	v_mul_f32_e32 v13, v13, v25
	v_bfe_u32 v22, v10, 16, 1
	v_bfe_u32 v24, v12, 16, 1
	v_bfe_u32 v23, v11, 16, 1
	v_bfe_u32 v25, v13, 16, 1
	v_add3_u32 v10, v10, v22, s26
	v_add3_u32 v12, v12, v24, s26
	v_add3_u32 v11, v11, v23, s26
	v_add3_u32 v13, v13, v25, s26
	v_lshrrev_b32_e32 v10, 16, v10
	v_lshrrev_b32_e32 v12, 16, v12
	v_and_or_b32 v10, v11, s27, v10
	v_and_or_b32 v11, v13, s27, v12
	global_store_dwordx2 v62, v[10:11], s[4:5] offset:3584
	v_mov_b32_e32 v22, v132
	v_mov_b32_e32 v23, v133
	v_mov_b32_e32 v24, v134
	v_mov_b32_e32 v25, v135
	v_mul_f32_e32 v12, v50, v77
	v_mul_f32_e32 v13, v51, v77
	v_lshl_add_u64 v[10:11], s[4:5], 0, v[62:63]
	v_add_co_u32_e32 v10, vcc, s23, v10
	v_mul_f32_e32 v12, v12, v22
	v_mul_f32_e32 v22, v30, v24
	v_mul_f32_e32 v13, v13, v23
	v_mul_f32_e32 v23, v31, v25
	v_bfe_u32 v24, v12, 16, 1
	v_bfe_u32 v30, v22, 16, 1
	v_bfe_u32 v25, v13, 16, 1
	v_bfe_u32 v31, v23, 16, 1
	v_add3_u32 v12, v12, v24, s26
	v_add3_u32 v22, v22, v30, s26
	v_add3_u32 v13, v13, v25, s26
	v_add3_u32 v23, v23, v31, s26
	v_lshrrev_b32_e32 v12, 16, v12
	v_lshrrev_b32_e32 v22, 16, v22
	v_addc_co_u32_e32 v11, vcc, 0, v11, vcc
	v_and_or_b32 v12, v13, s27, v12
	v_and_or_b32 v13, v23, s27, v22
	global_store_dwordx2 v[10:11], v[12:13], off
	v_mov_b32_e32 v22, v136
	v_mov_b32_e32 v23, v137
	v_mov_b32_e32 v24, v138
	v_mov_b32_e32 v25, v139
	v_mul_f32_e32 v12, v42, v77
	v_mul_f32_e32 v30, v44, v77
	v_mul_f32_e32 v13, v43, v77
	v_mul_f32_e32 v31, v45, v77
	v_mul_f32_e32 v12, v12, v22
	v_mul_f32_e32 v22, v30, v24
	v_mul_f32_e32 v13, v13, v23
	v_mul_f32_e32 v23, v31, v25
	v_bfe_u32 v24, v12, 16, 1
	v_bfe_u32 v30, v22, 16, 1
	v_bfe_u32 v25, v13, 16, 1
	v_bfe_u32 v31, v23, 16, 1
	v_add3_u32 v12, v12, v24, s26
	v_add3_u32 v22, v22, v30, s26
	v_add3_u32 v13, v13, v25, s26
	v_add3_u32 v23, v23, v31, s26
	v_lshrrev_b32_e32 v12, 16, v12
	v_lshrrev_b32_e32 v22, 16, v22
	v_and_or_b32 v12, v13, s27, v12
	v_and_or_b32 v13, v23, s27, v22
	global_store_dwordx2 v[10:11], v[12:13], off offset:512
	v_mov_b32_e32 v22, v140
	v_mov_b32_e32 v23, v141
	v_mov_b32_e32 v24, v142
	v_mov_b32_e32 v25, v143
	v_mul_f32_e32 v12, v38, v77
	v_mul_f32_e32 v30, v40, v77
	v_mul_f32_e32 v13, v39, v77
	v_mul_f32_e32 v31, v41, v77
	v_mul_f32_e32 v12, v12, v22
	v_mul_f32_e32 v22, v30, v24
	v_mul_f32_e32 v13, v13, v23
	v_mul_f32_e32 v23, v31, v25
	v_bfe_u32 v24, v12, 16, 1
	v_bfe_u32 v30, v22, 16, 1
	v_bfe_u32 v25, v13, 16, 1
	v_bfe_u32 v31, v23, 16, 1
	v_add3_u32 v12, v12, v24, s26
	v_add3_u32 v22, v22, v30, s26
	v_add3_u32 v13, v13, v25, s26
	v_add3_u32 v23, v23, v31, s26
	v_lshrrev_b32_e32 v12, 16, v12
	v_lshrrev_b32_e32 v22, 16, v22
	v_and_or_b32 v12, v13, s27, v12
	v_and_or_b32 v13, v23, s27, v22
	global_store_dwordx2 v[10:11], v[12:13], off offset:1024
	v_mov_b32_e32 v22, v144
	v_mov_b32_e32 v23, v145
	v_mov_b32_e32 v24, v146
	v_mov_b32_e32 v25, v147
	v_mul_f32_e32 v12, v26, v77
	v_mul_f32_e32 v26, v28, v77
	v_mul_f32_e32 v13, v27, v77
	v_mul_f32_e32 v27, v29, v77
	v_add_co_u32_e32 v30, vcc, s24, v54
	v_mul_f32_e32 v12, v12, v22
	v_mul_f32_e32 v22, v26, v24
	v_mul_f32_e32 v13, v13, v23
	v_mul_f32_e32 v23, v27, v25
	v_bfe_u32 v24, v12, 16, 1
	v_bfe_u32 v26, v22, 16, 1
	v_bfe_u32 v25, v13, 16, 1
	v_bfe_u32 v27, v23, 16, 1
	v_add3_u32 v12, v12, v24, s26
	v_add3_u32 v22, v22, v26, s26
	v_add3_u32 v13, v13, v25, s26
	v_add3_u32 v23, v23, v27, s26
	v_lshrrev_b32_e32 v12, 16, v12
	v_lshrrev_b32_e32 v22, 16, v22
	v_and_or_b32 v12, v13, s27, v12
	v_and_or_b32 v13, v23, s27, v22
	v_addc_co_u32_e32 v31, vcc, 0, v55, vcc
	global_store_dwordx2 v[10:11], v[12:13], off offset:1536
	v_mov_b32_e32 v22, v148
	v_mov_b32_e32 v23, v149
	v_mov_b32_e32 v24, v150
	v_mov_b32_e32 v25, v151
	v_mul_f32_e32 v12, v18, v77
	v_mul_f32_e32 v18, v20, v77
	v_mul_f32_e32 v13, v19, v77
	v_mul_f32_e32 v19, v21, v77
	v_mul_f32_e32 v12, v12, v22
	v_mul_f32_e32 v18, v18, v24
	v_mul_f32_e32 v13, v13, v23
	v_mul_f32_e32 v19, v19, v25
	v_bfe_u32 v20, v12, 16, 1
	v_bfe_u32 v22, v18, 16, 1
	v_bfe_u32 v21, v13, 16, 1
	v_bfe_u32 v23, v19, 16, 1
	v_add3_u32 v12, v12, v20, s26
	v_add3_u32 v18, v18, v22, s26
	v_add3_u32 v13, v13, v21, s26
	v_add3_u32 v19, v19, v23, s26
	v_lshrrev_b32_e32 v12, 16, v12
	v_lshrrev_b32_e32 v18, 16, v18
	v_and_or_b32 v12, v13, s27, v12
	v_and_or_b32 v13, v19, s27, v18
	global_store_dwordx2 v[10:11], v[12:13], off offset:2048
	v_mov_b32_e32 v18, v152
	v_mov_b32_e32 v19, v153
	v_mov_b32_e32 v20, v154
	v_mov_b32_e32 v21, v155
	v_mul_f32_e32 v12, v14, v77
	v_mul_f32_e32 v14, v16, v77
	v_mul_f32_e32 v13, v15, v77
	v_mul_f32_e32 v15, v17, v77
	v_mul_f32_e32 v12, v12, v18
	v_mul_f32_e32 v14, v14, v20
	v_mul_f32_e32 v13, v13, v19
	v_mul_f32_e32 v15, v15, v21
	v_bfe_u32 v16, v12, 16, 1
	v_bfe_u32 v18, v14, 16, 1
	v_bfe_u32 v17, v13, 16, 1
	v_bfe_u32 v19, v15, 16, 1
	v_add3_u32 v12, v12, v16, s26
	v_add3_u32 v14, v14, v18, s26
	v_add3_u32 v13, v13, v17, s26
	v_add3_u32 v15, v15, v19, s26
	v_lshrrev_b32_e32 v12, 16, v12
	v_lshrrev_b32_e32 v14, 16, v14
	v_and_or_b32 v12, v13, s27, v12
	v_and_or_b32 v13, v15, s27, v14
	global_store_dwordx2 v[10:11], v[12:13], off offset:2560
	v_mov_b32_e32 v12, v156
	v_mov_b32_e32 v13, v157
	v_mov_b32_e32 v14, v158
	v_mov_b32_e32 v15, v159
	v_mul_f32_e32 v6, v6, v12
	v_mul_f32_e32 v8, v8, v14
	v_mul_f32_e32 v7, v7, v13
	v_mul_f32_e32 v9, v9, v15
	v_bfe_u32 v12, v6, 16, 1
	v_bfe_u32 v14, v8, 16, 1
	v_bfe_u32 v13, v7, 16, 1
	v_bfe_u32 v15, v9, 16, 1
	v_add3_u32 v6, v6, v12, s26
	v_add3_u32 v8, v8, v14, s26
	v_add3_u32 v7, v7, v13, s26
	v_add3_u32 v9, v9, v15, s26
	v_lshrrev_b32_e32 v6, 16, v6
	v_lshrrev_b32_e32 v8, 16, v8
	v_and_or_b32 v6, v7, s27, v6
	v_and_or_b32 v7, v9, s27, v8
	global_store_dwordx2 v[10:11], v[6:7], off offset:3072
	v_mov_b32_e32 v6, v160
	v_mov_b32_e32 v7, v161
	v_mov_b32_e32 v8, v162
	v_mov_b32_e32 v9, v163
	v_mul_f32_e32 v2, v2, v6
	v_mul_f32_e32 v4, v4, v8
	v_mul_f32_e32 v3, v3, v7
	v_mul_f32_e32 v5, v5, v9
	v_bfe_u32 v6, v2, 16, 1
	v_bfe_u32 v8, v4, 16, 1
	v_bfe_u32 v7, v3, 16, 1
	v_bfe_u32 v9, v5, 16, 1
	v_add3_u32 v2, v2, v6, s26
	v_add3_u32 v4, v4, v8, s26
	v_add3_u32 v3, v3, v7, s26
	v_add3_u32 v5, v5, v9, s26
	v_lshrrev_b32_e32 v2, 16, v2
	v_lshrrev_b32_e32 v4, 16, v4
	v_and_or_b32 v2, v3, s27, v2
	v_and_or_b32 v3, v5, s27, v4
	global_store_dwordx2 v[10:11], v[2:3], off offset:3584
	s_cbranch_scc1 .LBB0_20
